# adaLN RMSNorm phase hand-written: gain/shift/scale vectors kept in registers per batch instead of re-fetched per row and chunk; same arithmetic
# speedup vs baseline: 1.1509x; 1.0188x over previous
.LBB0_179:
	v_lshrrev_b32_e32 v96, 6, v138
	v_and_b32_e32 v98, 63, v138
	v_readfirstlane_b32 s8, v96
	v_lshlrev_b32_e32 v104, 4, v98
	v_lshlrev_b32_e32 v105, 3, v98
	v_xor_b32_e32 v106, 32, v98
	v_lshlrev_b32_e32 v106, 2, v106
	v_xor_b32_e32 v107, 16, v98
	v_lshlrev_b32_e32 v107, 2, v107
	v_xor_b32_e32 v108, 8, v98
	v_lshlrev_b32_e32 v108, 2, v108
	v_xor_b32_e32 v110, 4, v98
	v_lshlrev_b32_e32 v110, 2, v110
	v_xor_b32_e32 v111, 2, v98
	v_lshlrev_b32_e32 v111, 2, v111
	v_xor_b32_e32 v112, 1, v98
	v_lshlrev_b32_e32 v112, 2, v112
	v_readlane_b32 s2, v207, 52
	v_readlane_b32 s3, v207, 53
	s_nop 0
	s_load_dword s18, s[2:3], 0x0
	s_lshl_b32 s9, s96, 2
	s_add_u32 s9, s9, s8
	s_waitcnt lgkmcnt(0)
	s_lshl_b32 s18, s18, 2
	s_lshl_b32 s2, s50, 12
	v_readlane_b32 s76, v207, 16
	v_readlane_b32 s77, v207, 17
	s_add_u32 s76, s76, s2
	s_addc_u32 s77, s77, 0
	s_mul_i32 s2, s50, 0x9000
	s_add_u32 s2, s2, 0x4000
	s_add_u32 s78, s94, s2
	s_addc_u32 s79, s95, 0
	s_add_u32 s80, s94, 0x1100000
	s_addc_u32 s81, s95, 0
	v_readlane_b32 s82, v207, 4
	v_readlane_b32 s83, v207, 5
	s_add_u32 s84, s94, 0xa700000
	s_addc_u32 s85, s95, 0
	v_readlane_b32 s86, v207, 8
	v_readlane_b32 s87, v207, 9
	s_add_u32 s88, s94, 0xa500000
	s_addc_u32 s89, s95, 0
	s_add_u32 s90, s94, 0xc700000
	s_addc_u32 s91, s95, 0
	global_load_dwordx4 v[16:19], v104, s[76:77]
	global_load_dwordx4 v[20:23], v104, s[76:77] offset:1024
	global_load_dwordx4 v[24:27], v104, s[76:77] offset:2048
	global_load_dwordx4 v[28:31], v104, s[76:77] offset:3072
	s_mov_b32 s16, -1
.Lnm_loop:
	s_cmpk_ge_u32 s9, 0x4200
	s_cbranch_scc1 .Lnm_done
	s_lshr_b32 s17, s9, 13
	s_min_u32 s17, s17, 2
	s_cmp_eq_u32 s17, s16
	s_cbranch_scc1 .Lnm_have_mv
	s_mov_b32 s16, s17
	s_mul_i32 s2, s17, 0x3000
	s_add_u32 s20, s78, s2
	s_addc_u32 s21, s79, 0
	s_add_u32 s12, s20, 0x1000
	s_addc_u32 s13, s21, 0
	global_load_dwordx4 v[32:35], v104, s[20:21]
	global_load_dwordx4 v[36:39], v104, s[20:21] offset:1024
	global_load_dwordx4 v[40:43], v104, s[20:21] offset:2048
	global_load_dwordx4 v[44:47], v104, s[20:21] offset:3072
	global_load_dwordx4 v[48:51], v104, s[12:13]
	global_load_dwordx4 v[52:55], v104, s[12:13] offset:1024
	global_load_dwordx4 v[56:59], v104, s[12:13] offset:2048
	global_load_dwordx4 v[60:63], v104, s[12:13] offset:3072
	s_waitcnt vmcnt(0)
	v_add_f32_e32 v48, 1.0, v48
	v_add_f32_e32 v49, 1.0, v49
	v_add_f32_e32 v50, 1.0, v50
	v_add_f32_e32 v51, 1.0, v51
	v_add_f32_e32 v52, 1.0, v52
	v_add_f32_e32 v53, 1.0, v53
	v_add_f32_e32 v54, 1.0, v54
	v_add_f32_e32 v55, 1.0, v55
	v_add_f32_e32 v56, 1.0, v56
	v_add_f32_e32 v57, 1.0, v57
	v_add_f32_e32 v58, 1.0, v58
	v_add_f32_e32 v59, 1.0, v59
	v_add_f32_e32 v60, 1.0, v60
	v_add_f32_e32 v61, 1.0, v61
	v_add_f32_e32 v62, 1.0, v62
	v_add_f32_e32 v63, 1.0, v63
.Lnm_have_mv:
	s_cmpk_lt_u32 s9, 0x4000
	s_cbranch_scc0 .Lnm_ctxrow
	s_cmp_eq_u32 s50, 0
	s_cbranch_scc0 .Lnm_bf16row
	s_lshl_b32 s2, s9, 12
	s_add_u32 s12, s82, s2
	s_addc_u32 s13, s83, 0
	global_load_dwordx4 v[0:3], v104, s[12:13] nt
	global_load_dwordx4 v[4:7], v104, s[12:13] offset:1024 nt
	global_load_dwordx4 v[8:11], v104, s[12:13] offset:2048 nt
	global_load_dwordx4 v[12:15], v104, s[12:13] offset:3072 nt
	s_branch .Lnm_loaded
.Lnm_bf16row:
	s_lshl_b32 s2, s9, 11
	s_add_u32 s12, s84, s2
	s_addc_u32 s13, s85, 0
	global_load_dwordx2 v[64:65], v105, s[12:13]
	global_load_dwordx2 v[66:67], v105, s[12:13] offset:512
	global_load_dwordx2 v[68:69], v105, s[12:13] offset:1024
	global_load_dwordx2 v[70:71], v105, s[12:13] offset:1536
	s_waitcnt vmcnt(0)
	v_lshlrev_b32_e32 v0, 16, v64
	v_and_b32_e32 v1, 0xffff0000, v64
	v_lshlrev_b32_e32 v2, 16, v65
	v_and_b32_e32 v3, 0xffff0000, v65
	v_lshlrev_b32_e32 v4, 16, v66
	v_and_b32_e32 v5, 0xffff0000, v66
	v_lshlrev_b32_e32 v6, 16, v67
	v_and_b32_e32 v7, 0xffff0000, v67
	v_lshlrev_b32_e32 v8, 16, v68
	v_and_b32_e32 v9, 0xffff0000, v68
	v_lshlrev_b32_e32 v10, 16, v69
	v_and_b32_e32 v11, 0xffff0000, v69
	v_lshlrev_b32_e32 v12, 16, v70
	v_and_b32_e32 v13, 0xffff0000, v70
	v_lshlrev_b32_e32 v14, 16, v71
	v_and_b32_e32 v15, 0xffff0000, v71
	s_branch .Lnm_math
.Lnm_ctxrow:
	s_sub_u32 s2, s9, 0x4000
	s_lshl_b32 s2, s2, 12
	s_add_u32 s12, s86, s2
	s_addc_u32 s13, s87, 0
	global_load_dwordx4 v[0:3], v104, s[12:13] nt
	global_load_dwordx4 v[4:7], v104, s[12:13] offset:1024 nt
	global_load_dwordx4 v[8:11], v104, s[12:13] offset:2048 nt
	global_load_dwordx4 v[12:15], v104, s[12:13] offset:3072 nt
	s_cmp_eq_u32 s50, 0
	s_cbranch_scc1 .Lnm_loaded
	s_add_u32 s12, s88, s2
	s_addc_u32 s13, s89, 0
	s_add_u32 s20, s90, s2
	s_addc_u32 s21, s91, 0
	global_load_dwordx4 v[64:67], v104, s[12:13]
	global_load_dwordx4 v[68:71], v104, s[12:13] offset:1024
	global_load_dwordx4 v[72:75], v104, s[12:13] offset:2048
	global_load_dwordx4 v[76:79], v104, s[12:13] offset:3072
	global_load_dwordx4 v[80:83], v104, s[20:21]
	global_load_dwordx4 v[84:87], v104, s[20:21] offset:1024
	global_load_dwordx4 v[88:91], v104, s[20:21] offset:2048
	global_load_dwordx4 v[92:95], v104, s[20:21] offset:3072
	s_waitcnt vmcnt(0)
	v_add_f32_e32 v64, v64, v80
	v_add_f32_e32 v65, v65, v81
	v_add_f32_e32 v66, v66, v82
	v_add_f32_e32 v67, v67, v83
	v_add_f32_e32 v68, v68, v84
	v_add_f32_e32 v69, v69, v85
	v_add_f32_e32 v70, v70, v86
	v_add_f32_e32 v71, v71, v87
	v_add_f32_e32 v72, v72, v88
	v_add_f32_e32 v73, v73, v89
	v_add_f32_e32 v74, v74, v90
	v_add_f32_e32 v75, v75, v91
	v_add_f32_e32 v76, v76, v92
	v_add_f32_e32 v77, v77, v93
	v_add_f32_e32 v78, v78, v94
	v_add_f32_e32 v79, v79, v95
	v_add_f32_e32 v0, v0, v64
	v_add_f32_e32 v1, v1, v65
	v_add_f32_e32 v2, v2, v66
	v_add_f32_e32 v3, v3, v67
	v_add_f32_e32 v4, v4, v68
	v_add_f32_e32 v5, v5, v69
	v_add_f32_e32 v6, v6, v70
	v_add_f32_e32 v7, v7, v71
	v_add_f32_e32 v8, v8, v72
	v_add_f32_e32 v9, v9, v73
	v_add_f32_e32 v10, v10, v74
	v_add_f32_e32 v11, v11, v75
	v_add_f32_e32 v12, v12, v76
	v_add_f32_e32 v13, v13, v77
	v_add_f32_e32 v14, v14, v78
	v_add_f32_e32 v15, v15, v79

.Lnm_math:
	v_mul_f32_e32 v98, v0, v0
	v_fmac_f32_e32 v98, v1, v1
	v_fmac_f32_e32 v98, v2, v2
	v_fmac_f32_e32 v98, v3, v3
	v_mov_b32_e32 v96, v98
	v_mul_f32_e32 v98, v4, v4
	v_fmac_f32_e32 v98, v5, v5
	v_fmac_f32_e32 v98, v6, v6
	v_fmac_f32_e32 v98, v7, v7
	v_add_f32_e32 v96, v96, v98
	v_mul_f32_e32 v98, v8, v8
	v_fmac_f32_e32 v98, v9, v9
	v_fmac_f32_e32 v98, v10, v10
	v_fmac_f32_e32 v98, v11, v11
	v_add_f32_e32 v96, v96, v98
	v_mul_f32_e32 v98, v12, v12
	v_fmac_f32_e32 v98, v13, v13
	v_fmac_f32_e32 v98, v14, v14
	v_fmac_f32_e32 v98, v15, v15
	v_add_f32_e32 v96, v96, v98
	ds_bpermute_b32 v98, v106, v96
	s_waitcnt lgkmcnt(0)
	v_add_f32_e32 v96, v96, v98
	ds_bpermute_b32 v98, v107, v96
	s_waitcnt lgkmcnt(0)
	v_add_f32_e32 v96, v96, v98
	ds_bpermute_b32 v98, v108, v96
	s_waitcnt lgkmcnt(0)
	v_add_f32_e32 v96, v96, v98
	ds_bpermute_b32 v98, v110, v96
	s_waitcnt lgkmcnt(0)
	v_add_f32_e32 v96, v96, v98
	ds_bpermute_b32 v98, v111, v96
	s_waitcnt lgkmcnt(0)
	v_add_f32_e32 v96, v96, v98
	ds_bpermute_b32 v98, v112, v96
	s_waitcnt lgkmcnt(0)
	v_add_f32_e32 v96, v96, v98
	v_fmamk_f32 v99, v96, 0x3a800000, v139
	v_mul_f32_e32 v98, 0x4b800000, v99
	v_cmp_gt_f32_e32 vcc, s33, v99
	s_nop 1
	v_cndmask_b32_e32 v99, v99, v98, vcc
	v_rsq_f32_e32 v99, v99
	s_nop 0
	v_mul_f32_e32 v98, 0x45800000, v99
	v_cndmask_b32_e32 v99, v99, v98, vcc
	s_lshl_b32 s2, s9, 11
	s_add_u32 s12, s80, s2
	s_addc_u32 s13, s81, 0
	v_mul_f32_e32 v0, v0, v99
	v_mul_f32_e32 v0, v16, v0
	v_fma_f32 v0, v0, v48, v32
	v_mul_f32_e32 v1, v1, v99
	v_mul_f32_e32 v1, v17, v1
	v_fma_f32 v1, v1, v49, v33
	v_mul_f32_e32 v2, v2, v99
	v_mul_f32_e32 v2, v18, v2
	v_fma_f32 v2, v2, v50, v34
	v_mul_f32_e32 v3, v3, v99
	v_mul_f32_e32 v3, v19, v3
	v_fma_f32 v3, v3, v51, v35
	v_cvt_pk_bf16_f32 v100, v0, v1
	v_cvt_pk_bf16_f32 v101, v2, v3
	global_store_dwordx2 v105, v[100:101], s[12:13]
	v_mul_f32_e32 v4, v4, v99
	v_mul_f32_e32 v4, v20, v4
	v_fma_f32 v4, v4, v52, v36
	v_mul_f32_e32 v5, v5, v99
	v_mul_f32_e32 v5, v21, v5
	v_fma_f32 v5, v5, v53, v37
	v_mul_f32_e32 v6, v6, v99
	v_mul_f32_e32 v6, v22, v6
	v_fma_f32 v6, v6, v54, v38
	v_mul_f32_e32 v7, v7, v99
	v_mul_f32_e32 v7, v23, v7
	v_fma_f32 v7, v7, v55, v39
	v_cvt_pk_bf16_f32 v100, v4, v5
	v_cvt_pk_bf16_f32 v101, v6, v7
	global_store_dwordx2 v105, v[100:101], s[12:13] offset:512
	v_mul_f32_e32 v8, v8, v99
	v_mul_f32_e32 v8, v24, v8
	v_fma_f32 v8, v8, v56, v40
	v_mul_f32_e32 v9, v9, v99
	v_mul_f32_e32 v9, v25, v9
	v_fma_f32 v9, v9, v57, v41
	v_mul_f32_e32 v10, v10, v99
	v_mul_f32_e32 v10, v26, v10
	v_fma_f32 v10, v10, v58, v42
	v_mul_f32_e32 v11, v11, v99
	v_mul_f32_e32 v11, v27, v11
	v_fma_f32 v11, v11, v59, v43
	v_cvt_pk_bf16_f32 v100, v8, v9
	v_cvt_pk_bf16_f32 v101, v10, v11
	global_store_dwordx2 v105, v[100:101], s[12:13] offset:1024
	v_mul_f32_e32 v12, v12, v99
	v_mul_f32_e32 v12, v28, v12
	v_fma_f32 v12, v12, v60, v44
	v_mul_f32_e32 v13, v13, v99
	v_mul_f32_e32 v13, v29, v13
	v_fma_f32 v13, v13, v61, v45
	v_mul_f32_e32 v14, v14, v99
	v_mul_f32_e32 v14, v30, v14
	v_fma_f32 v14, v14, v62, v46
	v_mul_f32_e32 v15, v15, v99
	v_mul_f32_e32 v15, v31, v15
	v_fma_f32 v15, v15, v63, v47
	v_cvt_pk_bf16_f32 v100, v12, v13
	v_cvt_pk_bf16_f32 v101, v14, v15
	global_store_dwordx2 v105, v[100:101], s[12:13] offset:1536
	s_add_u32 s9, s9, s18
	s_branch .Lnm_loop
.Lnm_done:
.LBB0_187:
	s_or_b64 exec, exec, s[12:13]
	v_readlane_b32 s0, v205, 9
	s_waitcnt vmcnt(0)
	v_readlane_b32 s1, v205, 10
	s_xor_b64 s[52:53], s[0:1], -1
	s_barrier
	s_mov_b64 s[0:1], exec
	v_readlane_b32 s2, v207, 0
	v_readlane_b32 s3, v207, 1
	v_readlane_b32 s4, v205, 16
	s_and_b64 s[2:3], s[0:1], s[2:3]
	v_readlane_b32 s5, v205, 17
	s_mov_b64 exec, s[2:3]
	s_cbranch_execz .LBB0_235
	s_waitcnt vmcnt(0) expcnt(0) lgkmcnt(0)
	ds_read_b32 v2, v140
	ds_read_b32 v0, v141
	s_waitcnt lgkmcnt(1)
	v_cmp_ne_u32_e32 vcc, 0, v2
	s_cbranch_vccnz .LBB0_203
	v_readlane_b32 s12, v207, 52
	v_readlane_b32 s13, v207, 53
	s_load_dwordx2 s[2:3], s[12:13], 0x0
	s_nop 0
	s_load_dword s12, s[12:13], 0x8
	s_mov_b32 s36, 1
	s_waitcnt lgkmcnt(0)
	s_mul_i32 s18, s3, s2
	s_mul_i32 s18, s18, s12
	s_branch .LBB0_191
